# phase-0 memory rows: second gain vector fetched at the iteration top under the row-type mask; the two vmcnt(0) round trips after the first output removed
# speedup vs baseline: 1.0066x; 1.0041x over previous
.LBB0_984:
	s_or_b64 exec, exec, s[2:3]
	v_lshlrev_b32_e32 v176, 2, v34
	v_lshl_add_u64 v[60:61], v[50:51], 0, v[176:177]
	v_lshl_add_u64 v[74:75], v[16:17], 0, v[176:177]
	global_load_dwordx4 v[52:55], v[60:61], off
	global_load_dwordx4 v[56:59], v[60:61], off offset:16
	global_load_dwordx4 v[66:69], v[60:61], off offset:2048
	global_load_dwordx4 v[70:73], v[60:61], off offset:2064
	v_cmp_ne_u64_e32 vcc, 0, v[38:39]
	s_and_saveexec_b64 s[8:9], vcc
	s_cbranch_execz .Lp0_nogb
	v_lshl_add_u64 v[94:95], v[38:39], 0, v[176:177]
	global_load_dwordx4 v[96:99], v[94:95], off offset:16
	global_load_dwordx4 v[100:103], v[94:95], off
	global_load_dwordx4 v[104:107], v[94:95], off offset:2064
	global_load_dwordx4 v[108:111], v[94:95], off offset:2048
.Lp0_nogb:
	s_or_b64 exec, exec, s[8:9]
	global_load_dwordx4 v[78:81], v[74:75], off offset:16
	global_load_dwordx4 v[82:85], v[74:75], off
	global_load_dwordx4 v[86:89], v[74:75], off offset:2064
	global_load_dwordx4 v[90:93], v[74:75], off offset:2048
	s_waitcnt vmcnt(4)
	v_mul_f32_e32 v18, v13, v13
	v_mul_f32_e32 v19, v9, v9
	v_mul_f32_e32 v20, v5, v5
	v_fmac_f32_e32 v18, v12, v12
	v_fmac_f32_e32 v19, v8, v8
	v_mul_f32_e32 v21, v1, v1
	v_fmac_f32_e32 v20, v4, v4
	v_fmac_f32_e32 v18, v14, v14
	v_fmac_f32_e32 v19, v10, v10
	v_fmac_f32_e32 v21, v0, v0
	v_fmac_f32_e32 v20, v6, v6
	v_fmac_f32_e32 v18, v15, v15
	v_fmac_f32_e32 v19, v11, v11
	v_fmac_f32_e32 v21, v2, v2
	v_fmac_f32_e32 v20, v7, v7
	v_add_f32_e32 v16, v18, v19
	v_fmac_f32_e32 v21, v3, v3
	v_add_f32_e32 v16, v16, v20
	v_add_f32_e32 v16, v16, v21
	v_lshlrev_b32_e32 v50, 1, v34
	v_mov_b32_e32 v51, v177
	v_add_f32_dpp v16, v16, v16 quad_perm:[1,0,3,2] row_mask:0xf bank_mask:0xf bound_ctrl:1
	v_lshl_add_u64 v[62:63], v[48:49], 0, v[50:51]
	s_nop 0
	v_add_f32_dpp v16, v16, v16 quad_perm:[2,3,0,1] row_mask:0xf bank_mask:0xf bound_ctrl:1
	s_nop 1
	v_add_f32_dpp v16, v16, v16 row_half_mirror row_mask:0xf bank_mask:0xf bound_ctrl:1
	s_nop 1
	v_add_f32_dpp v16, v16, v16 row_mirror row_mask:0xf bank_mask:0xf bound_ctrl:1
	v_mov_b32_e32 v17, v16
	s_nop 1
	v_permlane16_swap_b32_e32 v16, v17
	v_add_f32_e32 v16, v16, v17
	v_mov_b32_e32 v17, v16
	s_nop 1
	v_permlane32_swap_b32_e32 v16, v17
	v_add_f32_e32 v16, v16, v17
	v_fmamk_f32 v16, v16, 0x3a800000, v230
	v_mul_f32_e32 v17, 0x4b800000, v16
	v_cmp_gt_f32_e32 vcc, s91, v16
	s_nop 1
	v_cndmask_b32_e32 v16, v16, v17, vcc
	v_rsq_f32_e32 v33, v16
	s_nop 0
	v_mul_f32_e32 v35, 0x45800000, v33
	v_cndmask_b32_e32 v64, v33, v35, vcc
	v_mul_f32_e32 v48, v12, v64
	v_mul_f32_e32 v49, v13, v64
	v_mul_f32_e32 v14, v14, v64
	v_mul_f32_e32 v15, v15, v64
	v_mul_f32_e32 v12, v8, v64
	v_mul_f32_e32 v13, v9, v64
	v_mul_f32_e32 v10, v10, v64
	v_mul_f32_e32 v11, v11, v64
	v_mul_f32_e32 v6, v6, v64
	v_mul_f32_e32 v7, v7, v64
	v_cmp_ne_u64_e32 vcc, 0, v[38:39]
	v_mul_f32_e32 v8, v52, v48
	v_mul_f32_e32 v9, v53, v49
	v_mul_f32_e32 v54, v54, v14
	v_mul_f32_e32 v55, v55, v15
	v_mul_f32_e32 v56, v56, v12
	v_mul_f32_e32 v57, v57, v13
	v_mul_f32_e32 v58, v58, v10
	v_mul_f32_e32 v59, v59, v11
	v_cvt_pk_bf16_f32 v52, v8, v9
	v_cvt_pk_bf16_f32 v53, v54, v55
	v_cvt_pk_bf16_f32 v54, v56, v57
	v_cvt_pk_bf16_f32 v55, v58, v59
	global_store_dwordx4 v[62:63], v[52:55], off
	v_mul_f32_e32 v8, v4, v64
	v_mul_f32_e32 v9, v5, v64
	v_mul_f32_e32 v4, v0, v64
	v_mul_f32_e32 v5, v1, v64
	v_mul_f32_e32 v0, v2, v64
	v_mul_f32_e32 v1, v3, v64
	v_mul_f32_e32 v2, v66, v8
	v_mul_f32_e32 v3, v67, v9
	v_mul_f32_e32 v54, v68, v6
	v_mul_f32_e32 v55, v69, v7
	v_mul_f32_e32 v56, v70, v4
	v_mul_f32_e32 v57, v71, v5
	v_mul_f32_e32 v58, v72, v0
	v_mul_f32_e32 v59, v73, v1
	v_cvt_pk_bf16_f32 v52, v2, v3
	v_cvt_pk_bf16_f32 v53, v54, v55
	v_cvt_pk_bf16_f32 v54, v56, v57
	v_cvt_pk_bf16_f32 v55, v58, v59
	global_store_dwordx4 v[62:63], v[52:55], off offset:1024
	s_and_saveexec_b64 s[2:3], vcc
	s_cbranch_execz .LBB0_971
	v_lshl_add_u64 v[54:55], v[36:37], 0, v[50:51]
	v_mul_f32_e32 v12, v12, v96
	v_mul_f32_e32 v13, v13, v97
	v_mul_f32_e32 v48, v48, v100
	v_mul_f32_e32 v49, v49, v101
	v_mul_f32_e32 v14, v14, v102
	v_mul_f32_e32 v15, v15, v103
	v_mul_f32_e32 v10, v10, v98
	v_mul_f32_e32 v11, v11, v99
	v_cvt_pk_bf16_f32 v48, v48, v49
	v_cvt_pk_bf16_f32 v49, v14, v15
	v_cvt_pk_bf16_f32 v50, v12, v13
	v_cvt_pk_bf16_f32 v51, v10, v11
	global_store_dwordx4 v[54:55], v[48:51], off
	v_mul_f32_e32 v4, v4, v104
	v_mul_f32_e32 v5, v5, v105
	v_mul_f32_e32 v2, v8, v108
	v_mul_f32_e32 v3, v9, v109
	v_mul_f32_e32 v6, v6, v110
	v_mul_f32_e32 v7, v7, v111
	v_mul_f32_e32 v0, v0, v106
	v_mul_f32_e32 v1, v1, v107
	v_cvt_pk_bf16_f32 v2, v2, v3
	v_cvt_pk_bf16_f32 v3, v6, v7
	v_cvt_pk_bf16_f32 v4, v4, v5
	v_cvt_pk_bf16_f32 v5, v0, v1
	global_store_dwordx4 v[54:55], v[2:5], off offset:1024
	s_branch .LBB0_971
